# FFN-out GEMM (one tile per WG): the K-loop's trailing never-consumed stage loads re-read the two most recent K-tiles (cache-hot) instead of K-tiles 0/1
# baseline (speedup 1.0000x reference)
.LBB0_964:
	v_cndmask_b32_e64 v2, 0, 1, s[22:23]
	v_cmp_ne_u32_e64 s[6:7], 1, v2
	s_andn2_b64 vcc, exec, s[22:23]
	s_add_u32 s22, s44, 0x1500
	s_addc_u32 s23, s45, 0
	s_cbranch_vccnz .LBB0_966
	s_mul_i32 s22, s65, 0x160000
	s_mul_hi_i32 s23, s65, 0x160000
	s_add_u32 s22, s3, s22
	s_addc_u32 s23, s28, s23
.LBB0_966:
	s_and_b64 vcc, exec, s[6:7]
	s_add_u32 s24, s46, 0x1500
	s_addc_u32 s25, s47, 0
	s_cbranch_vccnz .LBB0_968
	s_mul_i32 s24, s66, 0x160000
	s_mul_hi_i32 s25, s66, 0x160000
	s_add_u32 s24, s29, s24
	s_addc_u32 s25, s30, s25

.LBB0_3301:
	v_cndmask_b32_e64 v2, 0, 1, s[40:41]
	v_cmp_ne_u32_e64 s[6:7], 1, v2
	s_andn2_b64 vcc, exec, s[40:41]
	s_add_u32 s42, s44, 0x1500
	s_addc_u32 s43, s45, 0
	s_cbranch_vccnz .LBB0_3303
	s_mul_i32 s42, s69, 0x160000
	s_mul_hi_i32 s43, s69, 0x160000
	s_add_u32 s42, s17, s42
	s_addc_u32 s43, s33, s43
.LBB0_3303:
	s_and_b64 vcc, exec, s[6:7]
	s_add_u32 s6, s46, 0x1500
	s_addc_u32 s7, s47, 0
	s_cbranch_vccnz .LBB0_3305
	s_mul_i32 s6, s70, 0x160000
	s_mul_hi_i32 s7, s70, 0x160000
	s_add_u32 s6, s34, s6
	s_addc_u32 s7, s35, s7

.LBB0_3571:
	v_cndmask_b32_e64 v2, 0, 1, s[24:25]
	v_cmp_ne_u32_e64 s[6:7], 1, v2
	s_andn2_b64 vcc, exec, s[24:25]
	s_add_u32 s44, s46, 0x1500
	s_addc_u32 s45, s47, 0
	s_cbranch_vccnz .LBB0_3573
	s_mul_i32 s44, s64, 0x160000
	s_mul_hi_i32 s45, s64, 0x160000
	s_add_u32 s44, s27, s44
	s_addc_u32 s45, s28, s45
.LBB0_3573:
	s_and_b64 vcc, exec, s[6:7]
	s_add_u32 s6, s48, 0x1500
	s_addc_u32 s7, s49, 0
	s_cbranch_vccnz .LBB0_3575
	s_mul_i32 s6, s65, 0x160000
	s_mul_hi_i32 s7, s65, 0x160000
	s_add_u32 s6, s29, s6
	s_addc_u32 s7, s30, s7

.LBB0_5908:
	v_cndmask_b32_e64 v2, 0, 1, s[22:23]
	v_cmp_ne_u32_e64 s[6:7], 1, v2
	s_andn2_b64 vcc, exec, s[22:23]
	s_add_u32 s24, s26, 0x1500
	s_addc_u32 s25, s27, 0
	s_cbranch_vccnz .LBB0_5910
	s_mul_i32 s24, s58, 0x160000
	s_mul_hi_i32 s25, s58, 0x160000
	s_add_u32 s24, s3, s24
	s_addc_u32 s25, s4, s25
.LBB0_5910:
	s_and_b64 vcc, exec, s[6:7]
	s_add_u32 s6, s34, 0x1500
	s_addc_u32 s7, s35, 0
	s_cbranch_vccnz .LBB0_5912
	s_mul_i32 s6, s59, 0x160000
	s_mul_hi_i32 s7, s59, 0x160000
	s_add_u32 s6, s5, s6
	s_addc_u32 s7, s33, s7
